# v8
# baseline (speedup 1.0000x reference)
; __device__ __forceinline__ s16x4 tr16(const u16* p) { return __builtin_amdgcn_ds_read_tr16_b64_v4i16((LAS s16x4*)p); }
; __device__ __forceinline__ bf16x8 cat8(s16x4 l, s16x4 h) { return (bf16x8){l[0], l[1], l[2], l[3], h[0], h[1], h[2], h[3]}; }
; __device__ __forceinline__ void ssd_phase(const Params& p, int j, char* smem) {
;     ...
;         for (int ks = 0; ks < 2; ++ks) {
;           const int sb = ks * 32 + fq * 8;
;           float wv[8];
;           *(float4*)&wv[0] = *(const float4*)(wS + hl * 64 + sb); *(float4*)&wv[4] = *(const float4*)(wS + hl * 64 + sb + 4);
;           bf16x8 xs[2];
;           for (int pt = 0; pt < 2; ++pt) {
;             float xv[8];
;             const u16* xp = XR + (sb + trr) * XR_LD + hl * 64 + ph * 32 + pt * 16 + trc;
;             unpack8(__builtin_bit_cast(uint4, cat8(tr16(xp), tr16(xp + 4 * XR_LD))), xv);
;             for (int i = 0; i < 8; ++i) xv[i] *= wv[i];
;             xs[pt] = as_bf16x8(pack8(xv));
;           }
;           for (int nt = 0; nt < 8; ++nt) {
;             const u16* bp = Bs + (sb + trr) * CS_LD + nt * 16 + trc;
;             bf16x8 ba = cat8(tr16(bp), tr16(bp + 4 * CS_LD));
;             for (int pt = 0; pt < 2; ++pt) hacc[nt][pt] = __builtin_amdgcn_mfma_f32_16x16x32_bf16(ba, xs[pt], hacc[nt][pt], 0, 0, 0);
;           }
;         }
.LBB0_309:
	v_or_b32_e32 v116, s37, v208
	v_lshl_add_u32 v120, v116, 2, v198
	v_or_b32_e32 v127, v116, v209
	ds_read_b128 v[116:119], v120
	ds_read_b128 v[120:123], v120 offset:16
	v_mad_u32_u24 v129, v127, s28, v210
	v_mad_u32_u24 v127, v127, s29, v125
	ds_read_b64_tr_b16 v[138:139], v129 offset:36928
	ds_read_b64_tr_b16 v[172:173], v129 offset:34816
	ds_read_b64_tr_b16 v[174:175], v129 offset:36960
	ds_read_b64_tr_b16 v[176:177], v129 offset:34848
	ds_read_b64_tr_b16 v[134:135], v127 offset:17408
	ds_read_b64_tr_b16 v[170:171], v127 offset:17440
	ds_read_b64_tr_b16 v[136:137], v127 offset:18496
	s_waitcnt lgkmcnt(8)
	v_mov_b32_e32 v178, v116
	v_mov_b32_e32 v179, v118
	v_mov_b32_e32 v118, v117
	s_waitcnt lgkmcnt(7)
	v_mov_b32_e32 v116, v120
	v_mov_b32_e32 v117, v122
	v_mov_b32_e32 v122, v121
	s_waitcnt lgkmcnt(5)
	v_lshlrev_b32_e32 v121, 16, v173
	v_lshlrev_b32_e32 v120, 16, v172
	v_and_b32_e32 v173, 0xffff0000, v173
	v_and_b32_e32 v172, 0xffff0000, v172
	s_waitcnt lgkmcnt(3)
	v_lshlrev_b32_e32 v181, 16, v177
	v_lshlrev_b32_e32 v180, 16, v176
	v_and_b32_e32 v177, 0xffff0000, v177
	v_and_b32_e32 v176, 0xffff0000, v176
	v_lshlrev_b32_e32 v183, 16, v139
	v_lshlrev_b32_e32 v182, 16, v138
	v_and_b32_e32 v139, 0xffff0000, v139
	v_and_b32_e32 v138, 0xffff0000, v138
	v_lshlrev_b32_e32 v185, 16, v175
	v_lshlrev_b32_e32 v184, 16, v174
	v_and_b32_e32 v175, 0xffff0000, v175
	v_and_b32_e32 v174, 0xffff0000, v174
	v_pk_mul_f32 v[172:173], v[118:119], v[172:173]
	v_pk_mul_f32 v[118:119], v[118:119], v[176:177]
	v_pk_mul_f32 v[176:177], v[116:117], v[182:183]
	v_pk_mul_f32 v[138:139], v[122:123], v[138:139]
	v_pk_mul_f32 v[116:117], v[116:117], v[184:185]
	v_pk_mul_f32 v[122:123], v[122:123], v[174:175]
	v_pk_mul_f32 v[120:121], v[178:179], v[120:121]
	v_pk_mul_f32 v[178:179], v[178:179], v[180:181]
	v_cvt_pk_bf16_f32 v118, v118, v119
	v_cvt_pk_bf16_f32 v133, v116, v117
	v_cvt_pk_bf16_f32 v116, v122, v123
	v_cvt_pk_bf16_f32 v120, v120, v121
	v_cvt_pk_bf16_f32 v121, v172, v173
	v_cvt_pk_bf16_f32 v129, v178, v179
	v_and_b32_e32 v123, 0xffff0000, v118
	v_lshlrev_b32_e32 v118, 16, v118
	v_lshlrev_b32_e32 v172, 16, v116
	v_cvt_pk_bf16_f32 v131, v138, v139
	v_and_b32_e32 v139, 0xffff0000, v116
	v_or_b32_sdwa v116, v118, v129 dst_sel:DWORD dst_unused:UNUSED_PAD src0_sel:DWORD src1_sel:WORD_0
	v_or_b32_sdwa v118, v172, v133 dst_sel:DWORD dst_unused:UNUSED_PAD src0_sel:DWORD src1_sel:WORD_0
	ds_read_b64_tr_b16 v[172:173], v127 offset:18528
	v_cvt_pk_bf16_f32 v119, v176, v177
	v_and_b32_e32 v117, 0xffff0000, v121
	v_lshlrev_b32_e32 v122, 16, v121
	v_and_b32_e32 v138, 0xffff0000, v131
	v_lshlrev_b32_e32 v131, 16, v131
	v_or_b32_sdwa v121, v117, v120 dst_sel:DWORD dst_unused:UNUSED_PAD src0_sel:DWORD src1_sel:WORD_1
	v_or_b32_sdwa v120, v122, v120 dst_sel:DWORD dst_unused:UNUSED_PAD src0_sel:DWORD src1_sel:WORD_0
	v_or_b32_sdwa v117, v123, v129 dst_sel:DWORD dst_unused:UNUSED_PAD src0_sel:DWORD src1_sel:WORD_1
	v_or_b32_sdwa v123, v138, v119 dst_sel:DWORD dst_unused:UNUSED_PAD src0_sel:DWORD src1_sel:WORD_1
	v_or_b32_sdwa v122, v131, v119 dst_sel:DWORD dst_unused:UNUSED_PAD src0_sel:DWORD src1_sel:WORD_0
	v_or_b32_sdwa v119, v139, v133 dst_sel:DWORD dst_unused:UNUSED_PAD src0_sel:DWORD src1_sel:WORD_1
	s_mov_b32 s37, 32
	s_waitcnt lgkmcnt(1)
	v_mfma_f32_16x16x32_bf16 v[8:11], v[134:137], v[120:123], v[8:11]
	s_andn2_b64 vcc, exec, s[92:93]
	s_mov_b64 s[92:93], 0
	v_mfma_f32_16x16x32_bf16 v[12:15], v[134:137], v[116:119], v[12:15]
	ds_read_b64_tr_b16 v[134:135], v127 offset:17472
	ds_read_b64_tr_b16 v[136:137], v127 offset:18560
	s_waitcnt lgkmcnt(2)
	v_mfma_f32_16x16x32_bf16 v[4:7], v[170:173], v[120:123], v[4:7]
	v_mfma_f32_16x16x32_bf16 v[16:19], v[170:173], v[116:119], v[16:19]
	ds_read_b64_tr_b16 v[172:173], v127 offset:18592
	ds_read_b64_tr_b16 v[170:171], v127 offset:17504
	s_waitcnt lgkmcnt(2)
	v_mfma_f32_16x16x32_bf16 v[20:23], v[134:137], v[120:123], v[20:23]
	v_mfma_f32_16x16x32_bf16 v[28:31], v[134:137], v[116:119], v[28:31]
	ds_read_b64_tr_b16 v[134:135], v127 offset:17536
	ds_read_b64_tr_b16 v[136:137], v127 offset:18624
	s_waitcnt lgkmcnt(2)
	v_mfma_f32_16x16x32_bf16 v[24:27], v[170:173], v[120:123], v[24:27]
	v_mfma_f32_16x16x32_bf16 v[32:35], v[170:173], v[116:119], v[32:35]
	ds_read_b64_tr_b16 v[172:173], v127 offset:18656
	ds_read_b64_tr_b16 v[170:171], v127 offset:17568
	s_waitcnt lgkmcnt(2)
	v_mfma_f32_16x16x32_bf16 v[36:39], v[134:137], v[120:123], v[36:39]
	v_mfma_f32_16x16x32_bf16 v[44:47], v[134:137], v[116:119], v[44:47]
	ds_read_b64_tr_b16 v[134:135], v127 offset:17600
	ds_read_b64_tr_b16 v[136:137], v127 offset:18688
	s_waitcnt lgkmcnt(2)
	v_mfma_f32_16x16x32_bf16 v[40:43], v[170:173], v[120:123], v[40:43]
	v_mfma_f32_16x16x32_bf16 v[48:51], v[170:173], v[116:119], v[48:51]
	ds_read_b64_tr_b16 v[172:173], v127 offset:18720
	ds_read_b64_tr_b16 v[170:171], v127 offset:17632
	s_waitcnt lgkmcnt(2)
	v_mfma_f32_16x16x32_bf16 v[52:55], v[134:137], v[120:123], v[52:55]
	v_mfma_f32_16x16x32_bf16 v[60:63], v[134:137], v[116:119], v[60:63]
	s_waitcnt lgkmcnt(0)
	v_mfma_f32_16x16x32_bf16 v[56:59], v[170:173], v[120:123], v[56:59]
	v_mfma_f32_16x16x32_bf16 v[64:67], v[170:173], v[116:119], v[64:67]
	s_cbranch_vccz .LBB0_309
; __device__ __forceinline__ float siluf(float x) { return x * __builtin_amdgcn_rcpf(1.f + __builtin_amdgcn_exp2f(x * -1.4426950408889634f)); }
; __device__ __forceinline__ void ssd_phase(const Params& p, int j, char* smem) {
;     ...
;       __syncthreads();
;       for (int i = 0; i < 4; ++i) {
;         const int id = tid_c + i * 512, t = id >> 5, oc = id & 31;
;         float yv[8], zv[8];
;         unpack8(*(const uint4*)(Ys + t * YS_LD + oc * 8), yv);
;         const bool ok = t < CL;
;         unpack8(zr4[i], zv);
;         float ss = 0.f;
;         for (int k = 0; k < 8; ++k) { yv[k] *= siluf(zv[k]); ss += yv[k] * yv[k]; }
;         for (int o = 16; o >= 1; o >>= 1) ss += __shfl_xor(ss, o);
;         const float rs = rsqrtf(ss * (1.f / 256.f) + EPS);
;         const float* nw = nwS + oc * 8;
;         float4 n0 = *(const float4*)nw, n1 = *(const float4*)(nw + 4);
;         float nv[8] = {n0.x, n0.y, n0.z, n0.w, n1.x, n1.y, n1.z, n1.w};
;         for (int k = 0; k < 8; ++k) yv[k] *= rs * nv[k];
;         if (ok) *(uint4*)(p.yn + (t0 + t) * DIN + g * 256 + oc * 8) = pack8(yv);
	s_waitcnt vmcnt(3)
	v_lshlrev_b32_e32 v134, 16, v112
	v_mul_f32_e32 v125, 0xbfb8aa3b, v134
	v_exp_f32_e32 v125, v125
	v_lshlrev_b32_e32 v135, 16, v113
	v_and_b32_e32 v112, 0xffff0000, v112
	v_and_b32_e32 v113, 0xffff0000, v113
	v_add_f32_e32 v125, 1.0, v125
	v_rcp_f32_e32 v136, v125
	v_mul_f32_e32 v125, 0xbfb8aa3b, v135
	v_exp_f32_e32 v125, v125
	v_lshlrev_b32_e32 v139, 16, v115
	v_lshlrev_b32_e32 v138, 16, v114
	v_and_b32_e32 v171, 0xffff0000, v115
	v_add_f32_e32 v125, 1.0, v125
	v_rcp_f32_e32 v137, v125
	v_mul_f32_e32 v125, 0xbfb8aa3b, v112
	v_exp_f32_e32 v125, v125
	v_and_b32_e32 v170, 0xffff0000, v114
	v_pk_mul_f32 v[134:135], v[136:137], v[134:135]
	v_mul_f32_e32 v114, 0xbfb8aa3b, v138
	v_add_f32_e32 v125, 1.0, v125
	v_rcp_f32_e32 v136, v125
	v_mul_f32_e32 v125, 0xbfb8aa3b, v113
	v_exp_f32_e32 v125, v125
	v_mul_f32_e32 v115, 0xbfb8aa3b, v139
	v_exp_f32_e32 v114, v114
	v_exp_f32_e32 v115, v115
	v_add_f32_e32 v125, 1.0, v125
	v_rcp_f32_e32 v137, v125
	v_mul_f32_e32 v125, 0xbfb8aa3b, v170
	v_add_f32_e32 v114, 1.0, v114
	v_add_f32_e32 v115, 1.0, v115
	v_exp_f32_e32 v125, v125
	v_rcp_f32_e32 v114, v114
	v_rcp_f32_e32 v115, v115
	s_add_i32 s37, 0, 0x15000
	v_lshl_add_u32 v116, v132, 1, s37
	v_lshl_add_u32 v117, v132, 2, s26
	v_add_f32_e32 v125, 1.0, v125
	v_mad_u64_u32 v[118:119], s[38:39], v130, s28, v[116:117]
	v_pk_mul_f32 v[114:115], v[114:115], v[138:139]
	v_rcp_f32_e32 v138, v125
	v_mul_f32_e32 v125, 0xbfb8aa3b, v171
	s_barrier
	ds_read_b128 v[120:123], v118
	v_exp_f32_e32 v125, v125
	v_pk_mul_f32 v[112:113], v[136:137], v[112:113]
	v_add_u32_e32 v127, 64, v206
	v_add_f32_e32 v125, 1.0, v125
	s_waitcnt lgkmcnt(0)
	v_lshlrev_b32_e32 v119, 16, v121
	v_lshlrev_b32_e32 v118, 16, v120
	v_and_b32_e32 v121, 0xffff0000, v121
	v_and_b32_e32 v120, 0xffff0000, v120
	v_rcp_f32_e32 v139, v125
	v_pk_mul_f32 v[118:119], v[134:135], v[118:119]
	v_pk_mul_f32 v[120:121], v[112:113], v[120:121]
	v_pk_mul_f32 v[134:135], v[118:119], v[118:119]
	v_pk_mul_f32 v[112:113], v[120:121], v[120:121]
	v_lshlrev_b32_e32 v137, 16, v123
	v_lshlrev_b32_e32 v136, 16, v122
	v_add_f32_e32 v112, v134, v112
	v_and_b32_e32 v123, 0xffff0000, v123
	v_and_b32_e32 v122, 0xffff0000, v122
	v_pk_mul_f32 v[114:115], v[114:115], v[136:137]
	v_pk_mul_f32 v[138:139], v[138:139], v[170:171]
	v_add_f32_e32 v112, v112, v135
	v_pk_mul_f32 v[136:137], v[114:115], v[114:115]
	v_pk_mul_f32 v[122:123], v[138:139], v[122:123]
	v_add_f32_e32 v112, v113, v112
	v_pk_mul_f32 v[138:139], v[122:123], v[122:123]
	v_add_f32_e32 v112, v136, v112
	v_xor_b32_e32 v113, 16, v228
	v_add_f32_e32 v112, v138, v112
	v_cmp_lt_i32_e32 vcc, v113, v127
	v_add_f32_e32 v112, v137, v112
	v_add_f32_e32 v112, v139, v112
	v_cndmask_b32_e32 v113, v228, v113, vcc
	v_lshlrev_b32_e32 v125, 2, v113
	ds_bpermute_b32 v113, v125, v112
	s_waitcnt lgkmcnt(0)
	v_add_f32_e32 v112, v112, v113
	v_xor_b32_e32 v113, 8, v228
	v_cmp_lt_i32_e32 vcc, v113, v127
	s_nop 1
	v_cndmask_b32_e32 v113, v228, v113, vcc
	v_lshlrev_b32_e32 v133, 2, v113
	s_nop 1
	v_mov_b32_dpp v113, v112 row_ror:8 row_mask:0xf bank_mask:0xf
	s_waitcnt lgkmcnt(0)
	v_add_f32_e32 v112, v112, v113
	v_xor_b32_e32 v113, 4, v228
	v_cmp_lt_i32_e32 vcc, v113, v127
	s_nop 1
	v_cndmask_b32_e32 v113, v228, v113, vcc
	v_lshlrev_b32_e32 v134, 2, v113
	s_nop 1
	v_mov_b32_dpp v113, v112 row_ror:4 row_mask:0xf bank_mask:0xf
	s_waitcnt lgkmcnt(0)
	v_add_f32_e32 v112, v112, v113
	v_xor_b32_e32 v113, 2, v228
	v_cmp_lt_i32_e32 vcc, v113, v127
	s_nop 1
	v_cndmask_b32_e32 v113, v228, v113, vcc
	v_lshlrev_b32_e32 v135, 2, v113
	s_nop 1
	v_mov_b32_dpp v113, v112 row_ror:2 row_mask:0xf bank_mask:0xf
	s_waitcnt lgkmcnt(0)
	v_add_f32_e32 v113, v112, v113
	v_xor_b32_e32 v112, 1, v228
	v_cmp_lt_i32_e32 vcc, v112, v127
	s_nop 1
	v_cndmask_b32_e32 v112, v228, v112, vcc
	v_lshlrev_b32_e32 v136, 2, v112
	s_nop 1
	v_mov_b32_dpp v127, v113 row_ror:1 row_mask:0xf bank_mask:0xf
	v_lshlrev_b32_e32 v112, 1, v132
	s_and_saveexec_b64 s[92:93], s[24:25]
	s_cbranch_execz .LBB0_312
	s_waitcnt lgkmcnt(0)
	v_add_f32_e32 v113, v113, v127
	v_fmamk_f32 v113, v113, 0x3b800000, v225
	v_mul_f32_e32 v127, 0x4b800000, v113
	v_cmp_gt_f32_e32 vcc, s46, v113
	ds_read_b128 v[170:173], v117
	ds_read_b128 v[174:177], v117 offset:16
	v_cndmask_b32_e32 v113, v113, v127, vcc
	v_rsq_f32_e32 v113, v113
	v_ashrrev_i32_e32 v131, 31, v130
	s_waitcnt lgkmcnt(1)
	v_mov_b32_e32 v138, v171
	v_mov_b32_e32 v139, v173
	v_mul_f32_e32 v127, 0x45800000, v113
	v_cndmask_b32_e32 v132, v113, v127, vcc
	v_lshl_add_u64 v[130:131], s[4:5], 0, v[130:131]
	v_pk_mul_f32 v[138:139], v[132:133], v[138:139] op_sel_hi:[0,1]
	v_mov_b32_e32 v171, v172
	v_lshlrev_b64 v[130:131], 12, v[130:131]
	v_pk_mul_f32 v[120:121], v[120:121], v[138:139]
	v_pk_mul_f32 v[138:139], v[132:133], v[170:171] op_sel_hi:[0,1]
	v_lshl_add_u64 v[130:131], s[34:35], 0, v[130:131]
	v_mov_b32_e32 v113, v1
	v_pk_mul_f32 v[118:119], v[118:119], v[138:139]
	v_lshl_add_u64 v[130:131], v[130:131], 0, v[112:113]
	v_cvt_pk_bf16_f32 v113, v118, v119
	v_cvt_pk_bf16_f32 v118, v120, v121
	s_waitcnt lgkmcnt(0)
	v_mov_b32_e32 v120, v175
	v_mov_b32_e32 v121, v177
	v_pk_mul_f32 v[120:121], v[132:133], v[120:121] op_sel_hi:[0,1]
	v_mov_b32_e32 v175, v176
	v_pk_mul_f32 v[120:121], v[122:123], v[120:121]
	v_pk_mul_f32 v[122:123], v[132:133], v[174:175] op_sel_hi:[0,1]
	v_and_b32_e32 v119, 0xffff0000, v118
	v_lshlrev_b32_e32 v118, 16, v118
	v_pk_mul_f32 v[114:115], v[114:115], v[122:123]
	v_or_b32_sdwa v119, v119, v113 dst_sel:DWORD dst_unused:UNUSED_PAD src0_sel:DWORD src1_sel:WORD_1
	v_or_b32_sdwa v118, v118, v113 dst_sel:DWORD dst_unused:UNUSED_PAD src0_sel:DWORD src1_sel:WORD_0
	v_cvt_pk_bf16_f32 v113, v114, v115
	v_cvt_pk_bf16_f32 v114, v120, v121
	v_and_b32_e32 v115, 0xffff0000, v114
	v_lshlrev_b32_e32 v114, 16, v114
	v_or_b32_sdwa v121, v115, v113 dst_sel:DWORD dst_unused:UNUSED_PAD src0_sel:DWORD src1_sel:WORD_1
	v_or_b32_sdwa v120, v114, v113 dst_sel:DWORD dst_unused:UNUSED_PAD src0_sel:DWORD src1_sel:WORD_0
	global_store_dwordx4 v[130:131], v[118:121], off
; __device__ __forceinline__ float siluf(float x) { return x * __builtin_amdgcn_rcpf(1.f + __builtin_amdgcn_exp2f(x * -1.4426950408889634f)); }
; __device__ __forceinline__ void ssd_phase(const Params& p, int j, char* smem) {
;     ...
;       for (int i = 0; i < 4; ++i) {
;         const int id = tid_c + i * 512, t = id >> 5, oc = id & 31;
;         float yv[8], zv[8];
;         unpack8(*(const uint4*)(Ys + t * YS_LD + oc * 8), yv);
;         const bool ok = t < CL;
;         unpack8(zr4[i], zv);
;         float ss = 0.f;
;         for (int k = 0; k < 8; ++k) { yv[k] *= siluf(zv[k]); ss += yv[k] * yv[k]; }
;         for (int o = 16; o >= 1; o >>= 1) ss += __shfl_xor(ss, o);
;         const float rs = rsqrtf(ss * (1.f / 256.f) + EPS);
;         const float* nw = nwS + oc * 8;
;         float4 n0 = *(const float4*)nw, n1 = *(const float4*)(nw + 4);
;         float nv[8] = {n0.x, n0.y, n0.z, n0.w, n1.x, n1.y, n1.z, n1.w};
;         for (int k = 0; k < 8; ++k) yv[k] *= rs * nv[k];
;         if (ok) *(uint4*)(p.yn + (t0 + t) * DIN + g * 256 + oc * 8) = pack8(yv);
.LBB0_312:
	s_or_b64 exec, exec, s[92:93]
	s_waitcnt vmcnt(2)
	v_lshlrev_b32_e32 v122, 16, v108
	v_mul_f32_e32 v113, 0xbfb8aa3b, v122
	v_exp_f32_e32 v113, v113
	v_mad_u64_u32 v[114:115], s[24:25], v128, s28, v[116:117]
	v_lshlrev_b32_e32 v123, 16, v109
	v_add_f32_e32 v113, 1.0, v113
	ds_read_b128 v[118:121], v114
	v_rcp_f32_e32 v114, v113
	v_mul_f32_e32 v113, 0xbfb8aa3b, v123
	v_exp_f32_e32 v113, v113
	v_and_b32_e32 v130, 0xffff0000, v108
	v_and_b32_e32 v131, 0xffff0000, v109
	s_waitcnt lgkmcnt(0)
	v_lshlrev_b32_e32 v109, 16, v119
	v_add_f32_e32 v113, 1.0, v113
	v_rcp_f32_e32 v115, v113
	v_mul_f32_e32 v113, 0xbfb8aa3b, v130
	v_exp_f32_e32 v113, v113
	v_lshlrev_b32_e32 v108, 16, v118
	v_pk_mul_f32 v[114:115], v[114:115], v[122:123]
	v_lshlrev_b32_e32 v138, 16, v110
	v_add_f32_e32 v113, 1.0, v113
	v_pk_mul_f32 v[108:109], v[114:115], v[108:109]
	v_rcp_f32_e32 v114, v113
	v_mul_f32_e32 v113, 0xbfb8aa3b, v131
	v_exp_f32_e32 v113, v113
	v_lshlrev_b32_e32 v139, 16, v111
	v_and_b32_e32 v171, 0xffff0000, v111
	v_and_b32_e32 v170, 0xffff0000, v110
	v_add_f32_e32 v113, 1.0, v113
	v_rcp_f32_e32 v115, v113
	v_mul_f32_e32 v113, 0xbfb8aa3b, v138
	v_exp_f32_e32 v113, v113
	v_and_b32_e32 v111, 0xffff0000, v119
	v_and_b32_e32 v110, 0xffff0000, v118
	v_pk_mul_f32 v[114:115], v[114:115], v[130:131]
	v_add_f32_e32 v113, 1.0, v113
	v_pk_mul_f32 v[110:111], v[114:115], v[110:111]
	v_lshlrev_b32_e32 v114, 16, v120
	v_and_b32_e32 v118, 0xffff0000, v120
	v_rcp_f32_e32 v120, v113
	v_mul_f32_e32 v113, 0xbfb8aa3b, v139
	v_exp_f32_e32 v113, v113
	v_lshlrev_b32_e32 v115, 16, v121
	v_and_b32_e32 v119, 0xffff0000, v121
	v_pk_mul_f32 v[122:123], v[108:109], v[108:109]
	v_add_f32_e32 v113, 1.0, v113
	v_rcp_f32_e32 v121, v113
	v_mul_f32_e32 v113, 0xbfb8aa3b, v170
	v_exp_f32_e32 v113, v113
	v_pk_mul_f32 v[130:131], v[110:111], v[110:111]
	v_pk_mul_f32 v[120:121], v[120:121], v[138:139]
	v_add_f32_e32 v113, 1.0, v113
	v_rcp_f32_e32 v138, v113
	v_mul_f32_e32 v113, 0xbfb8aa3b, v171
	v_exp_f32_e32 v113, v113
	v_pk_mul_f32 v[114:115], v[120:121], v[114:115]
	v_add_f32_e32 v113, 1.0, v113
	v_rcp_f32_e32 v139, v113
	v_add_f32_e32 v113, v122, v130
	v_add_f32_e32 v113, v113, v123
	v_pk_mul_f32 v[120:121], v[114:115], v[114:115]
	v_pk_mul_f32 v[138:139], v[138:139], v[170:171]
	v_add_f32_e32 v113, v131, v113
	v_pk_mul_f32 v[118:119], v[138:139], v[118:119]
	v_add_f32_e32 v113, v120, v113
	v_pk_mul_f32 v[138:139], v[118:119], v[118:119]
	s_nop 0
	v_add_f32_e32 v113, v138, v113
	v_add_f32_e32 v113, v121, v113
	v_add_f32_e32 v113, v139, v113
	ds_bpermute_b32 v120, v125, v113
	s_waitcnt lgkmcnt(0)
	v_add_f32_e32 v113, v113, v120
	s_nop 1
	v_mov_b32_dpp v120, v113 row_ror:8 row_mask:0xf bank_mask:0xf
	s_waitcnt lgkmcnt(0)
	v_add_f32_e32 v113, v113, v120
	s_nop 1
	v_mov_b32_dpp v120, v113 row_ror:4 row_mask:0xf bank_mask:0xf
	s_waitcnt lgkmcnt(0)
	v_add_f32_e32 v113, v113, v120
	s_nop 1
	v_mov_b32_dpp v120, v113 row_ror:2 row_mask:0xf bank_mask:0xf
	s_waitcnt lgkmcnt(0)
	v_add_f32_e32 v113, v113, v120
	s_nop 1
	v_mov_b32_dpp v120, v113 row_ror:1 row_mask:0xf bank_mask:0xf
	s_and_saveexec_b64 s[24:25], s[22:23]
	s_cbranch_execz .LBB0_314
	s_waitcnt lgkmcnt(0)
	v_add_f32_e32 v113, v113, v120
	v_fmamk_f32 v113, v113, 0x3b800000, v225
	v_mul_f32_e32 v120, 0x4b800000, v113
	v_cmp_gt_f32_e32 vcc, s46, v113
	v_ashrrev_i32_e32 v129, 31, v128
	s_nop 0
	v_cndmask_b32_e32 v113, v113, v120, vcc
	v_rsq_f32_e32 v113, v113
	v_lshl_add_u64 v[120:121], s[4:5], 0, v[128:129]
	v_lshlrev_b64 v[128:129], 12, v[120:121]
	v_lshl_add_u64 v[128:129], s[34:35], 0, v[128:129]
	v_mul_f32_e32 v122, 0x45800000, v113
	v_cndmask_b32_e32 v132, v113, v122, vcc
	ds_read_b128 v[120:123], v117
	v_mov_b32_e32 v113, v1
	v_lshl_add_u64 v[138:139], v[128:129], 0, v[112:113]
	ds_read_b128 v[128:131], v117 offset:16
	s_waitcnt lgkmcnt(1)
	v_mov_b32_e32 v170, v121
	v_mov_b32_e32 v171, v123
	v_mov_b32_e32 v121, v122
	v_pk_mul_f32 v[170:171], v[132:133], v[170:171] op_sel_hi:[0,1]
	v_pk_mul_f32 v[120:121], v[132:133], v[120:121] op_sel_hi:[0,1]
	v_pk_mul_f32 v[110:111], v[110:111], v[170:171]
	v_pk_mul_f32 v[108:109], v[108:109], v[120:121]
	s_nop 0
	v_cvt_pk_bf16_f32 v108, v108, v109
	v_cvt_pk_bf16_f32 v109, v110, v111
	v_and_b32_e32 v110, 0xffff0000, v109
	v_lshlrev_b32_e32 v111, 16, v109
	v_or_b32_sdwa v109, v110, v108 dst_sel:DWORD dst_unused:UNUSED_PAD src0_sel:DWORD src1_sel:WORD_1
	v_or_b32_sdwa v108, v111, v108 dst_sel:DWORD dst_unused:UNUSED_PAD src0_sel:DWORD src1_sel:WORD_0
	s_waitcnt lgkmcnt(0)
	v_mov_b32_e32 v110, v129
	v_mov_b32_e32 v111, v131
	v_pk_mul_f32 v[110:111], v[132:133], v[110:111] op_sel_hi:[0,1]
	v_mov_b32_e32 v129, v130
	v_pk_mul_f32 v[110:111], v[118:119], v[110:111]
	v_pk_mul_f32 v[118:119], v[132:133], v[128:129] op_sel_hi:[0,1]
	v_pk_mul_f32 v[114:115], v[114:115], v[118:119]
	v_cvt_pk_bf16_f32 v110, v110, v111
	v_cvt_pk_bf16_f32 v113, v114, v115
	v_and_b32_e32 v111, 0xffff0000, v110
	v_lshlrev_b32_e32 v110, 16, v110
	v_or_b32_sdwa v111, v111, v113 dst_sel:DWORD dst_unused:UNUSED_PAD src0_sel:DWORD src1_sel:WORD_1
	v_or_b32_sdwa v110, v110, v113 dst_sel:DWORD dst_unused:UNUSED_PAD src0_sel:DWORD src1_sel:WORD_0
	global_store_dwordx4 v[138:139], v[108:111], off
; __device__ __forceinline__ float siluf(float x) { return x * __builtin_amdgcn_rcpf(1.f + __builtin_amdgcn_exp2f(x * -1.4426950408889634f)); }
; __device__ __forceinline__ void ssd_phase(const Params& p, int j, char* smem) {
;     ...
;       for (int i = 0; i < 4; ++i) {
;         const int id = tid_c + i * 512, t = id >> 5, oc = id & 31;
;         float yv[8], zv[8];
;         unpack8(*(const uint4*)(Ys + t * YS_LD + oc * 8), yv);
;         const bool ok = t < CL;
;         unpack8(zr4[i], zv);
;         float ss = 0.f;
;         for (int k = 0; k < 8; ++k) { yv[k] *= siluf(zv[k]); ss += yv[k] * yv[k]; }
;         for (int o = 16; o >= 1; o >>= 1) ss += __shfl_xor(ss, o);
;         const float rs = rsqrtf(ss * (1.f / 256.f) + EPS);
;         const float* nw = nwS + oc * 8;
;         float4 n0 = *(const float4*)nw, n1 = *(const float4*)(nw + 4);
;         float nv[8] = {n0.x, n0.y, n0.z, n0.w, n1.x, n1.y, n1.z, n1.w};
;         for (int k = 0; k < 8; ++k) yv[k] *= rs * nv[k];
;         if (ok) *(uint4*)(p.yn + (t0 + t) * DIN + g * 256 + oc * 8) = pack8(yv);
.LBB0_314:
	s_or_b64 exec, exec, s[24:25]
	s_waitcnt vmcnt(1)
	v_lshlrev_b32_e32 v110, 16, v104
	v_mul_f32_e32 v113, 0xbfb8aa3b, v110
	v_exp_f32_e32 v113, v113
	v_lshlrev_b32_e32 v111, 16, v105
	v_mad_u64_u32 v[108:109], s[22:23], v126, s28, v[116:117]
	v_add_f32_e32 v113, 1.0, v113
	v_rcp_f32_e32 v122, v113
	v_mul_f32_e32 v113, 0xbfb8aa3b, v111
	v_exp_f32_e32 v113, v113
	v_lshlrev_b32_e32 v119, 16, v107
	v_lshlrev_b32_e32 v118, 16, v106
	v_and_b32_e32 v121, 0xffff0000, v107
	s_waitcnt lgkmcnt(0)
	v_and_b32_e32 v120, 0xffff0000, v106
	ds_read_b128 v[106:109], v108
	v_add_f32_e32 v113, 1.0, v113
	v_rcp_f32_e32 v123, v113
	v_and_b32_e32 v115, 0xffff0000, v105
	v_and_b32_e32 v114, 0xffff0000, v104
	s_waitcnt lgkmcnt(0)
	v_lshlrev_b32_e32 v105, 16, v107
	v_lshlrev_b32_e32 v104, 16, v106
	v_pk_mul_f32 v[110:111], v[122:123], v[110:111]
	v_and_b32_e32 v107, 0xffff0000, v107
	v_pk_mul_f32 v[104:105], v[110:111], v[104:105]
	v_mul_f32_e32 v110, 0xbfb8aa3b, v114
	v_mul_f32_e32 v111, 0xbfb8aa3b, v115
	v_exp_f32_e32 v110, v110
	v_exp_f32_e32 v111, v111
	v_and_b32_e32 v106, 0xffff0000, v106
	v_and_b32_e32 v129, 0xffff0000, v109
	v_add_f32_e32 v110, 1.0, v110
	v_add_f32_e32 v111, 1.0, v111
	v_rcp_f32_e32 v110, v110
	v_rcp_f32_e32 v111, v111
	v_and_b32_e32 v128, 0xffff0000, v108
	v_pk_mul_f32 v[122:123], v[104:105], v[104:105]
	v_pk_mul_f32 v[110:111], v[110:111], v[114:115]
	s_nop 0
	v_pk_mul_f32 v[106:107], v[110:111], v[106:107]
	v_lshlrev_b32_e32 v111, 16, v109
	v_lshlrev_b32_e32 v110, 16, v108
	v_mul_f32_e32 v108, 0xbfb8aa3b, v118
	v_mul_f32_e32 v109, 0xbfb8aa3b, v119
	v_exp_f32_e32 v108, v108
	v_exp_f32_e32 v109, v109
	v_pk_mul_f32 v[114:115], v[106:107], v[106:107]
	v_add_f32_e32 v108, 1.0, v108
	v_add_f32_e32 v109, 1.0, v109
	v_rcp_f32_e32 v108, v108
	v_rcp_f32_e32 v109, v109
	v_add_f32_e32 v113, v122, v114
	v_add_f32_e32 v113, v113, v123
	v_add_f32_e32 v113, v115, v113
	v_pk_mul_f32 v[108:109], v[108:109], v[118:119]
	s_nop 0
	v_pk_mul_f32 v[108:109], v[108:109], v[110:111]
	v_mul_f32_e32 v110, 0xbfb8aa3b, v120
	v_mul_f32_e32 v111, 0xbfb8aa3b, v121
	v_exp_f32_e32 v110, v110
	v_exp_f32_e32 v111, v111
	v_pk_mul_f32 v[118:119], v[108:109], v[108:109]
	v_add_f32_e32 v110, 1.0, v110
	v_add_f32_e32 v111, 1.0, v111
	v_rcp_f32_e32 v110, v110
	v_rcp_f32_e32 v111, v111
	v_add_f32_e32 v113, v118, v113
	v_pk_mul_f32 v[110:111], v[110:111], v[120:121]
	s_nop 0
	v_pk_mul_f32 v[110:111], v[110:111], v[128:129]
	s_nop 0
	v_pk_mul_f32 v[120:121], v[110:111], v[110:111]
	s_nop 0
	v_add_f32_e32 v113, v120, v113
	v_add_f32_e32 v113, v119, v113
	v_add_f32_e32 v113, v121, v113
	ds_bpermute_b32 v114, v125, v113
	s_waitcnt lgkmcnt(0)
	v_add_f32_e32 v113, v113, v114
	s_nop 1
	v_mov_b32_dpp v114, v113 row_ror:8 row_mask:0xf bank_mask:0xf
	s_waitcnt lgkmcnt(0)
	v_add_f32_e32 v113, v113, v114
	s_nop 1
	v_mov_b32_dpp v114, v113 row_ror:4 row_mask:0xf bank_mask:0xf
	s_waitcnt lgkmcnt(0)
	v_add_f32_e32 v113, v113, v114
	s_nop 1
	v_mov_b32_dpp v114, v113 row_ror:2 row_mask:0xf bank_mask:0xf
	s_waitcnt lgkmcnt(0)
	v_add_f32_e32 v113, v113, v114
	s_nop 1
	v_mov_b32_dpp v114, v113 row_ror:1 row_mask:0xf bank_mask:0xf
	s_and_saveexec_b64 s[22:23], s[20:21]
	s_cbranch_execz .LBB0_316
	s_waitcnt lgkmcnt(0)
	v_add_f32_e32 v113, v113, v114
	v_fmamk_f32 v113, v113, 0x3b800000, v225
	v_mul_f32_e32 v114, 0x4b800000, v113
	v_cmp_gt_f32_e32 vcc, s46, v113
	v_ashrrev_i32_e32 v127, 31, v126
	s_nop 0
	v_cndmask_b32_e32 v113, v113, v114, vcc
	v_rsq_f32_e32 v113, v113
	v_lshl_add_u64 v[114:115], s[4:5], 0, v[126:127]
	ds_read_b128 v[126:129], v117 offset:16
	v_lshlrev_b64 v[114:115], 12, v[114:115]
	v_mul_f32_e32 v118, 0x45800000, v113
	v_cndmask_b32_e32 v122, v113, v118, vcc
	ds_read_b128 v[118:121], v117
	v_lshl_add_u64 v[114:115], s[34:35], 0, v[114:115]
	v_mov_b32_e32 v113, v1
	v_lshl_add_u64 v[114:115], v[114:115], 0, v[112:113]
	s_waitcnt lgkmcnt(0)
	v_mov_b32_e32 v130, v119
	v_mov_b32_e32 v131, v121
	v_mov_b32_e32 v119, v120
	v_pk_mul_f32 v[130:131], v[122:123], v[130:131] op_sel_hi:[0,1]
	v_pk_mul_f32 v[118:119], v[122:123], v[118:119] op_sel_hi:[0,1]
	v_pk_mul_f32 v[106:107], v[106:107], v[130:131]
	v_pk_mul_f32 v[104:105], v[104:105], v[118:119]
	s_nop 0
	v_cvt_pk_bf16_f32 v104, v104, v105
	v_cvt_pk_bf16_f32 v105, v106, v107
	v_and_b32_e32 v106, 0xffff0000, v105
	v_lshlrev_b32_e32 v107, 16, v105
	v_or_b32_sdwa v105, v106, v104 dst_sel:DWORD dst_unused:UNUSED_PAD src0_sel:DWORD src1_sel:WORD_1
	v_or_b32_sdwa v104, v107, v104 dst_sel:DWORD dst_unused:UNUSED_PAD src0_sel:DWORD src1_sel:WORD_0
	v_mov_b32_e32 v106, v127
	v_mov_b32_e32 v107, v129
	v_pk_mul_f32 v[106:107], v[122:123], v[106:107] op_sel_hi:[0,1]
	v_mov_b32_e32 v127, v128
	v_pk_mul_f32 v[106:107], v[110:111], v[106:107]
	v_pk_mul_f32 v[110:111], v[122:123], v[126:127] op_sel_hi:[0,1]
	v_pk_mul_f32 v[108:109], v[108:109], v[110:111]
	v_cvt_pk_bf16_f32 v106, v106, v107
	v_cvt_pk_bf16_f32 v108, v108, v109
	v_and_b32_e32 v107, 0xffff0000, v106
	v_lshlrev_b32_e32 v106, 16, v106
	v_or_b32_sdwa v107, v107, v108 dst_sel:DWORD dst_unused:UNUSED_PAD src0_sel:DWORD src1_sel:WORD_1
	v_or_b32_sdwa v106, v106, v108 dst_sel:DWORD dst_unused:UNUSED_PAD src0_sel:DWORD src1_sel:WORD_0
	global_store_dwordx4 v[114:115], v[104:107], off
; __device__ __forceinline__ float siluf(float x) { return x * __builtin_amdgcn_rcpf(1.f + __builtin_amdgcn_exp2f(x * -1.4426950408889634f)); }
; __device__ __forceinline__ void ssd_phase(const Params& p, int j, char* smem) {
;     ...
;       for (int i = 0; i < 4; ++i) {
;         const int id = tid_c + i * 512, t = id >> 5, oc = id & 31;
;         float yv[8], zv[8];
;         unpack8(*(const uint4*)(Ys + t * YS_LD + oc * 8), yv);
;         const bool ok = t < CL;
;         unpack8(zr4[i], zv);
;         float ss = 0.f;
;         for (int k = 0; k < 8; ++k) { yv[k] *= siluf(zv[k]); ss += yv[k] * yv[k]; }
;         for (int o = 16; o >= 1; o >>= 1) ss += __shfl_xor(ss, o);
;         const float rs = rsqrtf(ss * (1.f / 256.f) + EPS);
;         const float* nw = nwS + oc * 8;
;         float4 n0 = *(const float4*)nw, n1 = *(const float4*)(nw + 4);
;         float nv[8] = {n0.x, n0.y, n0.z, n0.w, n1.x, n1.y, n1.z, n1.w};
;         for (int k = 0; k < 8; ++k) yv[k] *= rs * nv[k];
;         if (ok) *(uint4*)(p.yn + (t0 + t) * DIN + g * 256 + oc * 8) = pack8(yv);
.LBB0_316:
	s_or_b64 exec, exec, s[22:23]
	s_waitcnt vmcnt(0)
	v_lshlrev_b32_e32 v106, 16, v100
	v_mul_f32_e32 v113, 0xbfb8aa3b, v106
	v_exp_f32_e32 v113, v113
	v_lshlrev_b32_e32 v107, 16, v101
	v_mad_u64_u32 v[104:105], s[20:21], v124, s28, v[116:117]
	v_add_f32_e32 v113, 1.0, v113
	v_rcp_f32_e32 v118, v113
	v_mul_f32_e32 v113, 0xbfb8aa3b, v107
	v_exp_f32_e32 v113, v113
	v_lshlrev_b32_e32 v111, 16, v103
	v_lshlrev_b32_e32 v110, 16, v102
	v_and_b32_e32 v115, 0xffff0000, v103
	s_waitcnt lgkmcnt(0)
	v_and_b32_e32 v114, 0xffff0000, v102
	ds_read_b128 v[102:105], v104
	v_add_f32_e32 v113, 1.0, v113
	v_rcp_f32_e32 v119, v113
	v_and_b32_e32 v109, 0xffff0000, v101
	v_and_b32_e32 v108, 0xffff0000, v100
	s_waitcnt lgkmcnt(0)
	v_lshlrev_b32_e32 v101, 16, v103
	v_lshlrev_b32_e32 v100, 16, v102
	v_pk_mul_f32 v[106:107], v[118:119], v[106:107]
	v_and_b32_e32 v103, 0xffff0000, v103
	v_pk_mul_f32 v[100:101], v[106:107], v[100:101]
	v_mul_f32_e32 v106, 0xbfb8aa3b, v108
	v_mul_f32_e32 v107, 0xbfb8aa3b, v109
	v_exp_f32_e32 v106, v106
	v_exp_f32_e32 v107, v107
	v_and_b32_e32 v102, 0xffff0000, v102
	v_and_b32_e32 v121, 0xffff0000, v105
	v_add_f32_e32 v106, 1.0, v106
	v_add_f32_e32 v107, 1.0, v107
	v_rcp_f32_e32 v106, v106
	v_rcp_f32_e32 v107, v107
	v_and_b32_e32 v120, 0xffff0000, v104
	v_pk_mul_f32 v[118:119], v[100:101], v[100:101]
	v_pk_mul_f32 v[106:107], v[106:107], v[108:109]
	s_nop 0
	v_pk_mul_f32 v[102:103], v[106:107], v[102:103]
	v_lshlrev_b32_e32 v107, 16, v105
	v_lshlrev_b32_e32 v106, 16, v104
	v_mul_f32_e32 v104, 0xbfb8aa3b, v110
	v_mul_f32_e32 v105, 0xbfb8aa3b, v111
	v_exp_f32_e32 v104, v104
	v_exp_f32_e32 v105, v105
	v_pk_mul_f32 v[108:109], v[102:103], v[102:103]
	v_add_f32_e32 v104, 1.0, v104
	v_add_f32_e32 v105, 1.0, v105
	v_rcp_f32_e32 v104, v104
	v_rcp_f32_e32 v105, v105
	v_add_f32_e32 v108, v118, v108
	v_add_f32_e32 v108, v108, v119
	v_add_f32_e32 v108, v109, v108
	v_pk_mul_f32 v[104:105], v[104:105], v[110:111]
	s_nop 0
	v_pk_mul_f32 v[104:105], v[104:105], v[106:107]
	v_mul_f32_e32 v106, 0xbfb8aa3b, v114
	v_mul_f32_e32 v107, 0xbfb8aa3b, v115
	v_exp_f32_e32 v106, v106
	v_exp_f32_e32 v107, v107
	v_pk_mul_f32 v[110:111], v[104:105], v[104:105]
	v_add_f32_e32 v106, 1.0, v106
	v_add_f32_e32 v107, 1.0, v107
	v_rcp_f32_e32 v106, v106
	v_rcp_f32_e32 v107, v107
	v_add_f32_e32 v108, v110, v108
	v_pk_mul_f32 v[106:107], v[106:107], v[114:115]
	s_nop 0
	v_pk_mul_f32 v[106:107], v[106:107], v[120:121]
	s_nop 0
	v_pk_mul_f32 v[114:115], v[106:107], v[106:107]
	s_nop 0
	v_add_f32_e32 v108, v114, v108
	v_add_f32_e32 v108, v111, v108
	v_add_f32_e32 v108, v115, v108
	ds_bpermute_b32 v109, v125, v108
	s_waitcnt lgkmcnt(0)
	v_add_f32_e32 v108, v108, v109
	s_nop 1
	v_mov_b32_dpp v109, v108 row_ror:8 row_mask:0xf bank_mask:0xf
	s_waitcnt lgkmcnt(0)
	v_add_f32_e32 v108, v108, v109
	s_nop 1
	v_mov_b32_dpp v109, v108 row_ror:4 row_mask:0xf bank_mask:0xf
	s_waitcnt lgkmcnt(0)
	v_add_f32_e32 v108, v108, v109
	s_nop 1
	v_mov_b32_dpp v109, v108 row_ror:2 row_mask:0xf bank_mask:0xf
	s_waitcnt lgkmcnt(0)
	v_add_f32_e32 v108, v108, v109
	s_nop 1
	v_mov_b32_dpp v109, v108 row_ror:1 row_mask:0xf bank_mask:0xf
	s_and_saveexec_b64 s[20:21], s[18:19]
	s_cbranch_execz .LBB0_318
	s_waitcnt lgkmcnt(0)
	v_add_f32_e32 v108, v108, v109
	v_fmamk_f32 v108, v108, 0x3b800000, v225
	v_mul_f32_e32 v109, 0x4b800000, v108
	v_cmp_gt_f32_e32 vcc, s46, v108
	v_ashrrev_i32_e32 v125, 31, v124
	v_mov_b32_e32 v113, v1
	v_cndmask_b32_e32 v108, v108, v109, vcc
	v_rsq_f32_e32 v110, v108
	v_lshl_add_u64 v[108:109], s[4:5], 0, v[124:125]
	v_lshlrev_b64 v[114:115], 12, v[108:109]
	v_lshl_add_u64 v[114:115], s[34:35], 0, v[114:115]
	v_mul_f32_e32 v111, 0x45800000, v110
	v_cndmask_b32_e32 v116, v110, v111, vcc
	ds_read_b128 v[108:111], v117
	v_lshl_add_u64 v[118:119], v[114:115], 0, v[112:113]
	ds_read_b128 v[112:115], v117 offset:16
	s_waitcnt lgkmcnt(1)
	v_mov_b32_e32 v120, v109
	v_mov_b32_e32 v121, v111
	v_mov_b32_e32 v109, v110
	v_pk_mul_f32 v[120:121], v[116:117], v[120:121] op_sel_hi:[0,1]
	v_pk_mul_f32 v[108:109], v[116:117], v[108:109] op_sel_hi:[0,1]
	v_pk_mul_f32 v[102:103], v[102:103], v[120:121]
	v_pk_mul_f32 v[100:101], v[100:101], v[108:109]
	s_nop 0
	v_cvt_pk_bf16_f32 v100, v100, v101
	v_cvt_pk_bf16_f32 v101, v102, v103
	v_and_b32_e32 v102, 0xffff0000, v101
	v_lshlrev_b32_e32 v103, 16, v101
	v_or_b32_sdwa v101, v102, v100 dst_sel:DWORD dst_unused:UNUSED_PAD src0_sel:DWORD src1_sel:WORD_1
	v_or_b32_sdwa v100, v103, v100 dst_sel:DWORD dst_unused:UNUSED_PAD src0_sel:DWORD src1_sel:WORD_0
	s_waitcnt lgkmcnt(0)
	v_mov_b32_e32 v102, v113
	v_mov_b32_e32 v103, v115
	v_pk_mul_f32 v[102:103], v[116:117], v[102:103] op_sel_hi:[0,1]
	v_mov_b32_e32 v113, v114
	v_pk_mul_f32 v[102:103], v[106:107], v[102:103]
	v_pk_mul_f32 v[106:107], v[116:117], v[112:113] op_sel_hi:[0,1]
	v_pk_mul_f32 v[104:105], v[104:105], v[106:107]
	v_cvt_pk_bf16_f32 v102, v102, v103
	v_cvt_pk_bf16_f32 v104, v104, v105
	v_and_b32_e32 v103, 0xffff0000, v102
	v_lshlrev_b32_e32 v102, 16, v102
	v_or_b32_sdwa v103, v103, v104 dst_sel:DWORD dst_unused:UNUSED_PAD src0_sel:DWORD src1_sel:WORD_1
	v_or_b32_sdwa v102, v102, v104 dst_sel:DWORD dst_unused:UNUSED_PAD src0_sel:DWORD src1_sel:WORD_0
	global_store_dwordx4 v[118:119], v[100:103], off
